# conv fix-up phase: the 8 conv-weight/bias loads per item issued together with one wait instead of 6 serialized load+vmcnt(0) steps
# speedup vs baseline: 1.0063x; 1.0041x over previous
.LBB0_150:
	s_or_b64 exec, exec, s[52:53]
	v_ashrrev_i32_e32 v31, 31, v30
	v_lshlrev_b64 v[40:41], 2, v[30:31]
	v_lshl_add_u64 v[32:33], s[12:13], 0, v[40:41]
	v_lshl_add_u64 v[36:37], s[24:25], 0, v[40:41]
	v_lshl_add_u64 v[44:45], s[26:27], 0, v[40:41]
	v_lshl_add_u64 v[48:49], s[20:21], 0, v[40:41]
	v_lshl_add_u64 v[52:53], s[30:31], 0, v[40:41]
	v_lshl_add_u64 v[56:57], s[42:43], 0, v[40:41]
	v_lshl_add_u64 v[60:61], s[46:47], 0, v[40:41]
	v_lshl_add_u64 v[84:85], s[48:49], 0, v[40:41]
	global_load_dwordx4 v[32:35], v[32:33], off
	global_load_dwordx4 v[36:39], v[36:37], off
	global_load_dwordx4 v[44:47], v[44:45], off
	global_load_dwordx4 v[48:51], v[48:49], off
	global_load_dwordx4 v[52:55], v[52:53], off
	global_load_dwordx4 v[56:59], v[56:57], off
	global_load_dwordx4 v[60:63], v[60:61], off
	global_load_dwordx4 v[84:87], v[84:85], off
	v_readlane_b32 s6, v255, 30
	v_readlane_b32 s7, v255, 31
	v_add_u32_e32 v26, s0, v26
	v_add_u32_e32 v28, s1, v28
	s_waitcnt vmcnt(0)
	v_pk_mul_f32 v[20:21], v[20:21], v[36:37]
	v_pk_mul_f32 v[22:23], v[22:23], v[38:39]
	v_pk_fma_f32 v[20:21], v[12:13], v[32:33], v[20:21]
	v_pk_fma_f32 v[22:23], v[14:15], v[34:35], v[22:23]
	v_pk_fma_f32 v[16:17], v[16:17], v[44:45], v[20:21]
	v_pk_fma_f32 v[18:19], v[18:19], v[46:47], v[22:23]
	v_pk_add_f32 v[22:23], v[48:49], v[16:17]
	v_pk_add_f32 v[20:21], v[50:51], v[18:19]
	v_pk_mul_f32 v[8:9], v[8:9], v[56:57]
	v_pk_mul_f32 v[10:11], v[10:11], v[58:59]
	v_pk_fma_f32 v[8:9], v[0:1], v[52:53], v[8:9]
	v_pk_fma_f32 v[10:11], v[2:3], v[54:55], v[10:11]
	v_pk_fma_f32 v[4:5], v[4:5], v[60:61], v[8:9]
	v_pk_fma_f32 v[6:7], v[6:7], v[62:63], v[10:11]
	v_pk_add_f32 v[0:1], v[84:85], v[4:5]
	s_nop 0
	v_mul_f32_e32 v4, 0xbfb8aa3b, v0
	v_exp_f32_e32 v4, v4
	v_pk_add_f32 v[2:3], v[86:87], v[6:7]
	v_add_f32_e32 v4, 1.0, v4
	v_rcp_f32_e32 v4, v4
	s_nop 0
	v_mul_f32_e32 v0, v0, v4
	v_mul_f32_e32 v4, 0xbfb8aa3b, v1
	v_exp_f32_e32 v4, v4
	v_mul_f32_e32 v0, v22, v0
	v_add_f32_e32 v4, 1.0, v4
	v_rcp_f32_e32 v4, v4
	s_nop 0
	v_mul_f32_e32 v1, v1, v4
	v_mul_f32_e32 v1, v23, v1
	v_cvt_pk_bf16_f32 v0, v0, v1
	v_mul_f32_e32 v1, 0xbfb8aa3b, v2
	v_exp_f32_e32 v1, v1
	s_nop 0
	v_add_f32_e32 v1, 1.0, v1
	v_rcp_f32_e32 v1, v1
	s_nop 0
	v_mul_f32_e32 v1, v2, v1
	v_mul_f32_e32 v2, 0xbfb8aa3b, v3
	v_exp_f32_e32 v2, v2
	v_mul_f32_e32 v1, v20, v1
	v_add_f32_e32 v2, 1.0, v2
	v_rcp_f32_e32 v2, v2
	s_nop 0
	v_mul_f32_e32 v2, v3, v2
	v_mul_f32_e32 v2, v21, v2
	v_cvt_pk_bf16_f32 v1, v1, v2
	v_mov_b64_e32 v[2:3], s[6:7]
	s_movk_i32 s6, 0x2c00
	v_mad_i64_i32 v[2:3], s[6:7], v27, s6, v[2:3]
	v_readlane_b32 s6, v253, 24
	v_readlane_b32 s7, v253, 25
	v_lshl_add_u64 v[2:3], v[30:31], 1, v[2:3]
	global_store_dwordx2 v[2:3], v[0:1], off
	v_lshl_add_u64 v[24:25], v[24:25], 0, s[6:7]
	s_mov_b64 s[6:7], 0x107fff
	v_cmp_lt_i64_e32 vcc, s[6:7], v[24:25]
	s_or_b64 s[50:51], vcc, s[50:51]
	s_andn2_b64 exec, exec, s[50:51]
	s_cbranch_execz .LBB0_163
